# fox_cumsum: 8 forget-gate loads issued together with counted waits (was 8 dependent round trips); prep-phase critical path on the 16 cumsum workgroups
# baseline (speedup 1.0000x reference)
; DI void fox_cumsum(const Params& p, int e) {
;     ...
;     const float* FF = (const float*)(p.ws + E_FF) + (size_t)b * T_ * 8 + h;
;     float* FC = (float*)(p.ws + E_FC) + (size_t)bh * T_;
;     const float bias = p.in[8][e * 8 + h];
;     float v[8], s = 0.f;
; #pragma unroll
;     for (int i = 0; i < 8; ++i) { const float x = FF[(size_t)(tid * 8 + i) * 8] + bias; s += fminf(x, 0.f) - log1pf(__expf(-fabsf(x))); v[i] = s; }
.LBB0_1971:
	s_ashr_i32 s0, s2, 3
	s_ashr_i32 s1, s0, 31
	s_and_b32 s3, s2, 7
	s_lshl_b64 s[0:1], s[0:1], 17
	s_add_u32 s0, s9, s0
	s_addc_u32 s1, s10, s1
	s_lshl_b32 s4, s3, 2
	s_add_u32 s4, s0, s4
	s_addc_u32 s5, s1, 0
	s_or_b32 s0, s3, s8
	s_ashr_i32 s1, s0, 31
	s_lshl_b64 s[0:1], s[0:1], 2
	v_readlane_b32 s12, v253, 14
	v_readlane_b32 s13, v253, 15
	s_add_u32 s0, s12, s0
	s_addc_u32 s1, s13, s1
	v_lshl_add_u64 v[20:21], s[4:5], 0, v[2:3]
	global_load_dword v0, v1, s[0:1]
	s_mov_b32 s6, 0x3f2aaaab
	global_load_dword v52, v[20:21], off
	v_lshl_add_u64 v[50:51], s[4:5], 0, v[4:5]
	global_load_dword v53, v[50:51], off
	v_lshl_add_u64 v[50:51], s[4:5], 0, v[6:7]
	global_load_dword v54, v[50:51], off
	v_lshl_add_u64 v[50:51], s[4:5], 0, v[8:9]
	global_load_dword v55, v[50:51], off
	v_lshl_add_u64 v[50:51], s[4:5], 0, v[10:11]
	global_load_dword v56, v[50:51], off
	v_lshl_add_u64 v[50:51], s[4:5], 0, v[12:13]
	global_load_dword v57, v[50:51], off
	v_lshl_add_u64 v[50:51], s[4:5], 0, v[14:15]
	global_load_dword v58, v[50:51], off
	v_lshl_add_u64 v[50:51], s[4:5], 0, v[16:17]
	global_load_dword v59, v[50:51], off
	s_mov_b32 s7, 0x3f317218
	v_mov_b32_e32 v47, 0x3ecc95a3
	s_mov_b32 s3, 0x7f800000
	v_mov_b32_e32 v48, 0x7f800000
	v_mov_b32_e32 v49, 0x7fc00000
	s_mov_b32 s11, 0x33800000
	v_readlane_b32 s14, v253, 16
	v_readlane_b32 s15, v253, 17
	v_readlane_b32 s16, v253, 18
	v_readlane_b32 s17, v253, 19
	v_readlane_b32 s18, v253, 20
	v_readlane_b32 s19, v253, 21
	v_readlane_b32 s20, v253, 22
	v_readlane_b32 s21, v253, 23
	v_readlane_b32 s22, v253, 24
	v_readlane_b32 s23, v253, 25
	v_readlane_b32 s24, v253, 26
	v_readlane_b32 s25, v253, 27
	v_readlane_b32 s26, v253, 28
	v_readlane_b32 s27, v253, 29
	s_waitcnt vmcnt(7)
	v_mov_b32_e32 v20, v52
	v_add_f32_e32 v20, v0, v20
	v_min_f32_e32 v22, 0, v20
	v_mul_f32_e64 v20, |v20|, s85
	v_exp_f32_e32 v23, v20
	s_nop 0
	v_add_f32_e32 v24, 1.0, v23
	v_add_f32_e32 v20, -1.0, v24
	v_sub_f32_e32 v21, v20, v24
	v_add_f32_e32 v21, 1.0, v21
	v_sub_f32_e32 v20, v23, v20
	v_add_f32_e32 v25, v20, v21
	v_frexp_mant_f32_e32 v20, v24
	v_cmp_gt_f32_e64 s[0:1], s6, v20
	v_cvt_f64_f32_e32 v[20:21], v24
	v_frexp_exp_i32_f64_e32 v20, v[20:21]
	v_subbrev_co_u32_e64 v20, s[0:1], 0, v20, s[0:1]
	v_sub_u32_e32 v21, 0, v20
	v_ldexp_f32 v24, v24, v21
	v_ldexp_f32 v21, v25, v21
	v_add_f32_e32 v25, -1.0, v24
	v_add_f32_e32 v26, 1.0, v25
	v_sub_f32_e32 v26, v24, v26
	v_add_f32_e32 v26, v21, v26
	v_add_f32_e32 v27, v25, v26
	v_sub_f32_e32 v25, v27, v25
	v_sub_f32_e32 v25, v26, v25
	v_add_f32_e32 v26, 1.0, v24
	v_add_f32_e32 v36, -1.0, v26
	v_sub_f32_e32 v24, v24, v36
	v_add_f32_e32 v21, v21, v24
	v_add_f32_e32 v24, v26, v21
	v_sub_f32_e32 v26, v24, v26
	v_sub_f32_e32 v21, v21, v26
	v_rcp_f32_e32 v26, v24
	v_cvt_f32_i32_e32 v20, v20
	v_cmp_neq_f32_e64 s[0:1], s3, v23
	v_mul_f32_e32 v36, v27, v26
	v_mul_f32_e32 v37, v24, v36
	v_fma_f32 v38, v36, v24, -v37
	v_fmac_f32_e32 v38, v36, v21
	v_add_f32_e32 v39, v37, v38
	v_sub_f32_e32 v40, v27, v39
	v_sub_f32_e32 v27, v27, v40
	v_sub_f32_e32 v37, v39, v37
	v_sub_f32_e32 v27, v27, v39
	v_add_f32_e32 v25, v25, v27
	v_sub_f32_e32 v27, v37, v38
	v_add_f32_e32 v25, v27, v25
	v_add_f32_e32 v27, v40, v25
	v_mul_f32_e32 v37, v26, v27
	v_mul_f32_e32 v38, v24, v37
	v_fma_f32 v24, v37, v24, -v38
	v_fmac_f32_e32 v24, v37, v21
	v_sub_f32_e32 v21, v40, v27
	v_add_f32_e32 v21, v25, v21
	v_add_f32_e32 v25, v38, v24
	v_sub_f32_e32 v39, v27, v25
	v_sub_f32_e32 v27, v27, v39
	v_sub_f32_e32 v38, v25, v38
	v_sub_f32_e32 v25, v27, v25
	v_add_f32_e32 v21, v21, v25
	v_sub_f32_e32 v24, v38, v24
	v_add_f32_e32 v21, v24, v21
	v_add_f32_e32 v24, v36, v37
	v_add_f32_e32 v21, v39, v21
	v_sub_f32_e32 v25, v24, v36
	v_mul_f32_e32 v21, v26, v21
	v_sub_f32_e32 v25, v37, v25
	v_add_f32_e32 v21, v25, v21
	v_mul_f32_e32 v36, 0x3f317218, v20
	v_add_f32_e32 v25, v24, v21
	v_fma_f32 v37, v20, s7, -v36
	v_mul_f32_e32 v26, v25, v25
	v_fmac_f32_e32 v37, 0xb102e308, v20
	v_sub_f32_e32 v20, v25, v24
	v_fmamk_f32 v27, v26, 0x3e9b6dac, v47
	v_sub_f32_e32 v20, v21, v20
	v_add_f32_e32 v21, v36, v37
	v_fmaak_f32 v27, v26, v27, 0x3f2aaada
	v_sub_f32_e32 v24, v21, v36
	v_ldexp_f32 v36, v25, 1
	v_mul_f32_e32 v25, v25, v26
	v_mul_f32_e32 v25, v25, v27
	v_add_f32_e32 v26, v36, v25
	v_sub_f32_e32 v27, v26, v36
	v_ldexp_f32 v20, v20, 1
	v_sub_f32_e32 v25, v25, v27
	v_add_f32_e32 v20, v20, v25
	v_add_f32_e32 v25, v26, v20
	v_sub_f32_e32 v26, v25, v26
	v_sub_f32_e32 v20, v20, v26
	v_add_f32_e32 v26, v21, v25
	v_sub_f32_e32 v27, v26, v21
	v_sub_f32_e32 v36, v26, v27
	v_sub_f32_e32 v24, v37, v24
	v_sub_f32_e32 v21, v21, v36
	v_sub_f32_e32 v25, v25, v27
	v_add_f32_e32 v21, v25, v21
	v_add_f32_e32 v25, v24, v20
	v_sub_f32_e32 v27, v25, v24
	v_sub_f32_e32 v36, v25, v27
	v_sub_f32_e32 v24, v24, v36
	v_sub_f32_e32 v20, v20, v27
	v_add_f32_e32 v21, v25, v21
	v_add_f32_e32 v20, v20, v24
	v_add_f32_e32 v24, v26, v21
	v_sub_f32_e32 v25, v24, v26
	v_sub_f32_e32 v21, v21, v25
	v_add_f32_e32 v20, v20, v21
	v_add_f32_e32 v20, v24, v20
	v_cndmask_b32_e64 v20, v48, v20, s[0:1]
	v_cmp_ngt_f32_e64 s[0:1], -1.0, v23
	s_nop 1
	v_cndmask_b32_e64 v20, v49, v20, s[0:1]
	v_cmp_neq_f32_e64 s[0:1], -1.0, v23
	s_nop 1
	v_cndmask_b32_e64 v20, v248, v20, s[0:1]
	v_cmp_lt_f32_e64 s[0:1], |v23|, s11
	s_nop 1
	v_cndmask_b32_e64 v20, v20, v23, s[0:1]
	v_sub_f32_e32 v20, v22, v20
	v_lshl_add_u64 v[22:23], s[4:5], 0, v[4:5]
	v_add_f32_e32 v20, 0, v20
	s_waitcnt vmcnt(6)
; DI void fox_cumsum(const Params& p, int e) {
;     ...
;     for (int i = 0; i < 8; ++i) { const float x = FF[(size_t)(tid * 8 + i) * 8] + bias; s += fminf(x, 0.f) - log1pf(__expf(-fabsf(x))); v[i] = s; }
	v_mov_b32_e32 v21, v53
	v_add_f32_e32 v21, v0, v21
	v_min_f32_e32 v24, 0, v21
	v_mul_f32_e64 v21, |v21|, s85
	v_exp_f32_e32 v21, v21
	s_nop 0
	v_add_f32_e32 v25, 1.0, v21
	v_add_f32_e32 v22, -1.0, v25
	v_sub_f32_e32 v23, v22, v25
	v_add_f32_e32 v23, 1.0, v23
	v_sub_f32_e32 v22, v21, v22
	v_add_f32_e32 v26, v22, v23
	v_frexp_mant_f32_e32 v22, v25
	v_cmp_gt_f32_e64 s[0:1], s6, v22
	v_cvt_f64_f32_e32 v[22:23], v25
	v_frexp_exp_i32_f64_e32 v22, v[22:23]
	v_subbrev_co_u32_e64 v22, s[0:1], 0, v22, s[0:1]
	v_sub_u32_e32 v23, 0, v22
	v_ldexp_f32 v25, v25, v23
	v_ldexp_f32 v23, v26, v23
	v_add_f32_e32 v26, -1.0, v25
	v_add_f32_e32 v27, 1.0, v26
	v_sub_f32_e32 v27, v25, v27
	v_add_f32_e32 v27, v23, v27
	v_add_f32_e32 v36, v26, v27
	v_sub_f32_e32 v26, v36, v26
	v_sub_f32_e32 v26, v27, v26
	v_add_f32_e32 v27, 1.0, v25
	v_add_f32_e32 v37, -1.0, v27
	v_sub_f32_e32 v25, v25, v37
	v_add_f32_e32 v23, v23, v25
	v_add_f32_e32 v25, v27, v23
	v_sub_f32_e32 v27, v25, v27
	v_sub_f32_e32 v23, v23, v27
	v_rcp_f32_e32 v27, v25
	v_cvt_f32_i32_e32 v22, v22
	v_cmp_neq_f32_e64 s[0:1], s3, v21
	v_mul_f32_e32 v37, v36, v27
	v_mul_f32_e32 v38, v25, v37
	v_fma_f32 v39, v37, v25, -v38
	v_fmac_f32_e32 v39, v37, v23
	v_add_f32_e32 v40, v38, v39
	v_sub_f32_e32 v41, v36, v40
	v_sub_f32_e32 v36, v36, v41
	v_sub_f32_e32 v38, v40, v38
	v_sub_f32_e32 v36, v36, v40
	v_add_f32_e32 v26, v26, v36
	v_sub_f32_e32 v36, v38, v39
	v_add_f32_e32 v26, v36, v26
	v_add_f32_e32 v36, v41, v26
	v_mul_f32_e32 v38, v27, v36
	v_mul_f32_e32 v39, v25, v38
	v_fma_f32 v25, v38, v25, -v39
	v_fmac_f32_e32 v25, v38, v23
	v_sub_f32_e32 v23, v41, v36
	v_add_f32_e32 v23, v26, v23
	v_add_f32_e32 v26, v39, v25
	v_sub_f32_e32 v40, v36, v26
	v_sub_f32_e32 v36, v36, v40
	v_sub_f32_e32 v39, v26, v39
	v_sub_f32_e32 v26, v36, v26
	v_add_f32_e32 v23, v23, v26
	v_sub_f32_e32 v25, v39, v25
	v_add_f32_e32 v23, v25, v23
	v_add_f32_e32 v25, v37, v38
	v_add_f32_e32 v23, v40, v23
	v_sub_f32_e32 v26, v25, v37
	v_mul_f32_e32 v23, v27, v23
	v_sub_f32_e32 v26, v38, v26
	v_add_f32_e32 v23, v26, v23
	v_mul_f32_e32 v37, 0x3f317218, v22
	v_add_f32_e32 v26, v25, v23
	v_fma_f32 v38, v22, s7, -v37
	v_mul_f32_e32 v27, v26, v26
	v_fmac_f32_e32 v38, 0xb102e308, v22
	v_sub_f32_e32 v22, v26, v25
	v_fmamk_f32 v36, v27, 0x3e9b6dac, v47
	v_sub_f32_e32 v22, v23, v22
	v_add_f32_e32 v23, v37, v38
	v_fmaak_f32 v36, v27, v36, 0x3f2aaada
	v_sub_f32_e32 v25, v23, v37
	v_ldexp_f32 v37, v26, 1
	v_mul_f32_e32 v26, v26, v27
	v_mul_f32_e32 v26, v26, v36
	v_add_f32_e32 v27, v37, v26
	v_sub_f32_e32 v36, v27, v37
	v_ldexp_f32 v22, v22, 1
	v_sub_f32_e32 v26, v26, v36
	v_add_f32_e32 v22, v22, v26
	v_add_f32_e32 v26, v27, v22
	v_sub_f32_e32 v27, v26, v27
	v_sub_f32_e32 v22, v22, v27
	v_add_f32_e32 v27, v23, v26
	v_sub_f32_e32 v36, v27, v23
	v_sub_f32_e32 v37, v27, v36
	v_sub_f32_e32 v25, v38, v25
	v_sub_f32_e32 v23, v23, v37
	v_sub_f32_e32 v26, v26, v36
	v_add_f32_e32 v23, v26, v23
	v_add_f32_e32 v26, v25, v22
	v_sub_f32_e32 v36, v26, v25
	v_sub_f32_e32 v37, v26, v36
	v_sub_f32_e32 v25, v25, v37
	v_sub_f32_e32 v22, v22, v36
	v_add_f32_e32 v23, v26, v23
	v_add_f32_e32 v22, v22, v25
	v_add_f32_e32 v25, v27, v23
	v_sub_f32_e32 v26, v25, v27
	v_sub_f32_e32 v23, v23, v26
	v_add_f32_e32 v22, v22, v23
	v_add_f32_e32 v22, v25, v22
	v_cndmask_b32_e64 v22, v48, v22, s[0:1]
	v_cmp_ngt_f32_e64 s[0:1], -1.0, v21
	s_nop 1
	v_cndmask_b32_e64 v22, v49, v22, s[0:1]
	v_cmp_neq_f32_e64 s[0:1], -1.0, v21
	s_nop 1
	v_cndmask_b32_e64 v22, v248, v22, s[0:1]
	v_cmp_lt_f32_e64 s[0:1], |v21|, s11
	s_nop 1
	v_cndmask_b32_e64 v21, v22, v21, s[0:1]
	v_lshl_add_u64 v[22:23], s[4:5], 0, v[6:7]
	v_sub_f32_e32 v21, v24, v21
	v_add_f32_e32 v21, v20, v21
	s_waitcnt vmcnt(5)
	v_mov_b32_e32 v22, v54
	v_add_f32_e32 v22, v0, v22
	v_min_f32_e32 v24, 0, v22
	v_mul_f32_e64 v22, |v22|, s85
	v_exp_f32_e32 v25, v22
	s_nop 0
	v_add_f32_e32 v26, 1.0, v25
	v_add_f32_e32 v22, -1.0, v26
	v_sub_f32_e32 v23, v22, v26
	v_add_f32_e32 v23, 1.0, v23
	v_sub_f32_e32 v22, v25, v22
	v_add_f32_e32 v27, v22, v23
	v_frexp_mant_f32_e32 v22, v26
	v_cmp_gt_f32_e64 s[0:1], s6, v22
	v_cvt_f64_f32_e32 v[22:23], v26
	v_frexp_exp_i32_f64_e32 v22, v[22:23]
	v_subbrev_co_u32_e64 v22, s[0:1], 0, v22, s[0:1]
	v_sub_u32_e32 v23, 0, v22
	v_ldexp_f32 v26, v26, v23
	v_ldexp_f32 v23, v27, v23
	v_add_f32_e32 v27, -1.0, v26
	v_add_f32_e32 v36, 1.0, v27
	v_sub_f32_e32 v36, v26, v36
	v_add_f32_e32 v36, v23, v36
	v_add_f32_e32 v37, v27, v36
	v_sub_f32_e32 v27, v37, v27
	v_sub_f32_e32 v27, v36, v27
	v_add_f32_e32 v36, 1.0, v26
	v_add_f32_e32 v38, -1.0, v36
	v_sub_f32_e32 v26, v26, v38
	v_add_f32_e32 v23, v23, v26
	v_add_f32_e32 v26, v36, v23
	v_sub_f32_e32 v36, v26, v36
	v_sub_f32_e32 v23, v23, v36
	v_rcp_f32_e32 v36, v26
	v_cvt_f32_i32_e32 v22, v22
	v_cmp_neq_f32_e64 s[0:1], s3, v25
	v_mul_f32_e32 v38, v37, v36
	v_mul_f32_e32 v39, v26, v38
	v_fma_f32 v40, v38, v26, -v39
	v_fmac_f32_e32 v40, v38, v23
	v_add_f32_e32 v41, v39, v40
	v_sub_f32_e32 v42, v37, v41
	v_sub_f32_e32 v37, v37, v42
	v_sub_f32_e32 v39, v41, v39
	v_sub_f32_e32 v37, v37, v41
	v_add_f32_e32 v27, v27, v37
	v_sub_f32_e32 v37, v39, v40
	v_add_f32_e32 v27, v37, v27
	v_add_f32_e32 v37, v42, v27
	v_mul_f32_e32 v39, v36, v37
	v_mul_f32_e32 v40, v26, v39
	v_fma_f32 v26, v39, v26, -v40
	v_fmac_f32_e32 v26, v39, v23
	v_sub_f32_e32 v23, v42, v37
	v_add_f32_e32 v23, v27, v23
	v_add_f32_e32 v27, v40, v26
	v_sub_f32_e32 v41, v37, v27
	v_sub_f32_e32 v37, v37, v41
	v_sub_f32_e32 v40, v27, v40
	v_sub_f32_e32 v27, v37, v27
	v_add_f32_e32 v23, v23, v27
	v_sub_f32_e32 v26, v40, v26
	v_add_f32_e32 v23, v26, v23
	v_add_f32_e32 v26, v38, v39
	v_add_f32_e32 v23, v41, v23
	v_sub_f32_e32 v27, v26, v38
; DI void fox_cumsum(const Params& p, int e) {
;     ...
;     for (int i = 0; i < 8; ++i) { const float x = FF[(size_t)(tid * 8 + i) * 8] + bias; s += fminf(x, 0.f) - log1pf(__expf(-fabsf(x))); v[i] = s; }
	v_mul_f32_e32 v23, v36, v23
	v_sub_f32_e32 v27, v39, v27
	v_add_f32_e32 v23, v27, v23
	v_mul_f32_e32 v38, 0x3f317218, v22
	v_add_f32_e32 v27, v26, v23
	v_fma_f32 v39, v22, s7, -v38
	v_mul_f32_e32 v36, v27, v27
	v_fmac_f32_e32 v39, 0xb102e308, v22
	v_sub_f32_e32 v22, v27, v26
	v_fmamk_f32 v37, v36, 0x3e9b6dac, v47
	v_sub_f32_e32 v22, v23, v22
	v_add_f32_e32 v23, v38, v39
	v_fmaak_f32 v37, v36, v37, 0x3f2aaada
	v_sub_f32_e32 v26, v23, v38
	v_ldexp_f32 v38, v27, 1
	v_mul_f32_e32 v27, v27, v36
	v_mul_f32_e32 v27, v27, v37
	v_add_f32_e32 v36, v38, v27
	v_sub_f32_e32 v37, v36, v38
	v_ldexp_f32 v22, v22, 1
	v_sub_f32_e32 v27, v27, v37
	v_add_f32_e32 v22, v22, v27
	v_add_f32_e32 v27, v36, v22
	v_sub_f32_e32 v36, v27, v36
	v_sub_f32_e32 v22, v22, v36
	v_add_f32_e32 v36, v23, v27
	v_sub_f32_e32 v37, v36, v23
	v_sub_f32_e32 v38, v36, v37
	v_sub_f32_e32 v26, v39, v26
	v_sub_f32_e32 v23, v23, v38
	v_sub_f32_e32 v27, v27, v37
	v_add_f32_e32 v23, v27, v23
	v_add_f32_e32 v27, v26, v22
	v_sub_f32_e32 v37, v27, v26
	v_sub_f32_e32 v38, v27, v37
	v_sub_f32_e32 v26, v26, v38
	v_sub_f32_e32 v22, v22, v37
	v_add_f32_e32 v23, v27, v23
	v_add_f32_e32 v22, v22, v26
	v_add_f32_e32 v26, v36, v23
	v_sub_f32_e32 v27, v26, v36
	v_sub_f32_e32 v23, v23, v27
	v_add_f32_e32 v22, v22, v23
	v_add_f32_e32 v22, v26, v22
	v_cndmask_b32_e64 v22, v48, v22, s[0:1]
	v_cmp_ngt_f32_e64 s[0:1], -1.0, v25
	s_nop 1
	v_cndmask_b32_e64 v22, v49, v22, s[0:1]
	v_cmp_neq_f32_e64 s[0:1], -1.0, v25
	s_nop 1
	v_cndmask_b32_e64 v22, v248, v22, s[0:1]
	v_cmp_lt_f32_e64 s[0:1], |v25|, s11
	s_nop 1
	v_cndmask_b32_e64 v22, v22, v25, s[0:1]
	v_sub_f32_e32 v22, v24, v22
	v_lshl_add_u64 v[24:25], s[4:5], 0, v[8:9]
	v_add_f32_e32 v22, v21, v22
	s_waitcnt vmcnt(4)
	v_mov_b32_e32 v23, v55
	v_add_f32_e32 v23, v0, v23
	v_min_f32_e32 v26, 0, v23
	v_mul_f32_e64 v23, |v23|, s85
	v_exp_f32_e32 v23, v23
	s_nop 0
	v_add_f32_e32 v27, 1.0, v23
	v_add_f32_e32 v24, -1.0, v27
	v_sub_f32_e32 v25, v24, v27
	v_add_f32_e32 v25, 1.0, v25
	v_sub_f32_e32 v24, v23, v24
	v_add_f32_e32 v36, v24, v25
	v_frexp_mant_f32_e32 v24, v27
	v_cmp_gt_f32_e64 s[0:1], s6, v24
	v_cvt_f64_f32_e32 v[24:25], v27
	v_frexp_exp_i32_f64_e32 v24, v[24:25]
	v_subbrev_co_u32_e64 v24, s[0:1], 0, v24, s[0:1]
	v_sub_u32_e32 v25, 0, v24
	v_ldexp_f32 v27, v27, v25
	v_ldexp_f32 v25, v36, v25
	v_add_f32_e32 v36, -1.0, v27
	v_add_f32_e32 v37, 1.0, v36
	v_sub_f32_e32 v37, v27, v37
	v_add_f32_e32 v37, v25, v37
	v_add_f32_e32 v38, v36, v37
	v_sub_f32_e32 v36, v38, v36
	v_sub_f32_e32 v36, v37, v36
	v_add_f32_e32 v37, 1.0, v27
	v_add_f32_e32 v39, -1.0, v37
	v_sub_f32_e32 v27, v27, v39
	v_add_f32_e32 v25, v25, v27
	v_add_f32_e32 v27, v37, v25
	v_sub_f32_e32 v37, v27, v37
	v_sub_f32_e32 v25, v25, v37
	v_rcp_f32_e32 v37, v27
	v_cvt_f32_i32_e32 v24, v24
	v_cmp_neq_f32_e64 s[0:1], s3, v23
	v_mul_f32_e32 v39, v38, v37
	v_mul_f32_e32 v40, v27, v39
	v_fma_f32 v41, v39, v27, -v40
	v_fmac_f32_e32 v41, v39, v25
	v_add_f32_e32 v42, v40, v41
	v_sub_f32_e32 v43, v38, v42
	v_sub_f32_e32 v38, v38, v43
	v_sub_f32_e32 v40, v42, v40
	v_sub_f32_e32 v38, v38, v42
	v_add_f32_e32 v36, v36, v38
	v_sub_f32_e32 v38, v40, v41
	v_add_f32_e32 v36, v38, v36
	v_add_f32_e32 v38, v43, v36
	v_mul_f32_e32 v40, v37, v38
	v_mul_f32_e32 v41, v27, v40
	v_fma_f32 v27, v40, v27, -v41
	v_fmac_f32_e32 v27, v40, v25
	v_sub_f32_e32 v25, v43, v38
	v_add_f32_e32 v25, v36, v25
	v_add_f32_e32 v36, v41, v27
	v_sub_f32_e32 v42, v38, v36
	v_sub_f32_e32 v38, v38, v42
	v_sub_f32_e32 v41, v36, v41
	v_sub_f32_e32 v36, v38, v36
	v_add_f32_e32 v25, v25, v36
	v_sub_f32_e32 v27, v41, v27
	v_add_f32_e32 v25, v27, v25
	v_add_f32_e32 v27, v39, v40
	v_add_f32_e32 v25, v42, v25
	v_sub_f32_e32 v36, v27, v39
	v_mul_f32_e32 v25, v37, v25
	v_sub_f32_e32 v36, v40, v36
	v_add_f32_e32 v25, v36, v25
	v_mul_f32_e32 v39, 0x3f317218, v24
	v_add_f32_e32 v36, v27, v25
	v_fma_f32 v40, v24, s7, -v39
	v_mul_f32_e32 v37, v36, v36
	v_fmac_f32_e32 v40, 0xb102e308, v24
	v_sub_f32_e32 v24, v36, v27
	v_fmamk_f32 v38, v37, 0x3e9b6dac, v47
	v_sub_f32_e32 v24, v25, v24
	v_add_f32_e32 v25, v39, v40
	v_fmaak_f32 v38, v37, v38, 0x3f2aaada
	v_sub_f32_e32 v27, v25, v39
	v_ldexp_f32 v39, v36, 1
	v_mul_f32_e32 v36, v36, v37
	v_mul_f32_e32 v36, v36, v38
	v_add_f32_e32 v37, v39, v36
	v_sub_f32_e32 v38, v37, v39
	v_ldexp_f32 v24, v24, 1
	v_sub_f32_e32 v36, v36, v38
	v_add_f32_e32 v24, v24, v36
	v_add_f32_e32 v36, v37, v24
	v_sub_f32_e32 v37, v36, v37
	v_sub_f32_e32 v24, v24, v37
	v_add_f32_e32 v37, v25, v36
	v_sub_f32_e32 v38, v37, v25
	v_sub_f32_e32 v39, v37, v38
	v_sub_f32_e32 v27, v40, v27
	v_sub_f32_e32 v25, v25, v39
	v_sub_f32_e32 v36, v36, v38
	v_add_f32_e32 v25, v36, v25
	v_add_f32_e32 v36, v27, v24
	v_sub_f32_e32 v38, v36, v27
	v_sub_f32_e32 v39, v36, v38
	v_sub_f32_e32 v27, v27, v39
	v_sub_f32_e32 v24, v24, v38
	v_add_f32_e32 v25, v36, v25
	v_add_f32_e32 v24, v24, v27
	v_add_f32_e32 v27, v37, v25
	v_sub_f32_e32 v36, v27, v37
	v_sub_f32_e32 v25, v25, v36
	v_add_f32_e32 v24, v24, v25
	v_add_f32_e32 v24, v27, v24
	v_cndmask_b32_e64 v24, v48, v24, s[0:1]
	v_cmp_ngt_f32_e64 s[0:1], -1.0, v23
	s_nop 1
	v_cndmask_b32_e64 v24, v49, v24, s[0:1]
	v_cmp_neq_f32_e64 s[0:1], -1.0, v23
	s_nop 1
	v_cndmask_b32_e64 v24, v248, v24, s[0:1]
	v_cmp_lt_f32_e64 s[0:1], |v23|, s11
	s_nop 1
	v_cndmask_b32_e64 v23, v24, v23, s[0:1]
	v_lshl_add_u64 v[24:25], s[4:5], 0, v[10:11]
	v_sub_f32_e32 v23, v26, v23
	v_add_f32_e32 v23, v22, v23
	s_waitcnt vmcnt(3)
; DI void fox_cumsum(const Params& p, int e) {
;     ...
;     for (int i = 0; i < 8; ++i) { const float x = FF[(size_t)(tid * 8 + i) * 8] + bias; s += fminf(x, 0.f) - log1pf(__expf(-fabsf(x))); v[i] = s; }
	v_mov_b32_e32 v24, v56
	v_add_f32_e32 v24, v0, v24
	v_min_f32_e32 v26, 0, v24
	v_mul_f32_e64 v24, |v24|, s85
	v_exp_f32_e32 v27, v24
	s_nop 0
	v_add_f32_e32 v36, 1.0, v27
	v_add_f32_e32 v24, -1.0, v36
	v_sub_f32_e32 v25, v24, v36
	v_add_f32_e32 v25, 1.0, v25
	v_sub_f32_e32 v24, v27, v24
	v_add_f32_e32 v37, v24, v25
	v_frexp_mant_f32_e32 v24, v36
	v_cmp_gt_f32_e64 s[0:1], s6, v24
	v_cvt_f64_f32_e32 v[24:25], v36
	v_frexp_exp_i32_f64_e32 v24, v[24:25]
	v_subbrev_co_u32_e64 v24, s[0:1], 0, v24, s[0:1]
	v_sub_u32_e32 v25, 0, v24
	v_ldexp_f32 v36, v36, v25
	v_ldexp_f32 v25, v37, v25
	v_add_f32_e32 v37, -1.0, v36
	v_add_f32_e32 v38, 1.0, v37
	v_sub_f32_e32 v38, v36, v38
	v_add_f32_e32 v38, v25, v38
	v_add_f32_e32 v39, v37, v38
	v_sub_f32_e32 v37, v39, v37
	v_sub_f32_e32 v37, v38, v37
	v_add_f32_e32 v38, 1.0, v36
	v_add_f32_e32 v40, -1.0, v38
	v_sub_f32_e32 v36, v36, v40
	v_add_f32_e32 v25, v25, v36
	v_add_f32_e32 v36, v38, v25
	v_sub_f32_e32 v38, v36, v38
	v_sub_f32_e32 v25, v25, v38
	v_rcp_f32_e32 v38, v36
	v_cvt_f32_i32_e32 v24, v24
	v_cmp_neq_f32_e64 s[0:1], s3, v27
	v_mul_f32_e32 v40, v39, v38
	v_mul_f32_e32 v41, v36, v40
	v_fma_f32 v42, v40, v36, -v41
	v_fmac_f32_e32 v42, v40, v25
	v_add_f32_e32 v43, v41, v42
	v_sub_f32_e32 v44, v39, v43
	v_sub_f32_e32 v39, v39, v44
	v_sub_f32_e32 v41, v43, v41
	v_sub_f32_e32 v39, v39, v43
	v_add_f32_e32 v37, v37, v39
	v_sub_f32_e32 v39, v41, v42
	v_add_f32_e32 v37, v39, v37
	v_add_f32_e32 v39, v44, v37
	v_mul_f32_e32 v41, v38, v39
	v_mul_f32_e32 v42, v36, v41
	v_fma_f32 v36, v41, v36, -v42
	v_fmac_f32_e32 v36, v41, v25
	v_sub_f32_e32 v25, v44, v39
	v_add_f32_e32 v25, v37, v25
	v_add_f32_e32 v37, v42, v36
	v_sub_f32_e32 v43, v39, v37
	v_sub_f32_e32 v39, v39, v43
	v_sub_f32_e32 v42, v37, v42
	v_sub_f32_e32 v37, v39, v37
	v_add_f32_e32 v25, v25, v37
	v_sub_f32_e32 v36, v42, v36
	v_add_f32_e32 v25, v36, v25
	v_add_f32_e32 v36, v40, v41
	v_add_f32_e32 v25, v43, v25
	v_sub_f32_e32 v37, v36, v40
	v_mul_f32_e32 v25, v38, v25
	v_sub_f32_e32 v37, v41, v37
	v_add_f32_e32 v25, v37, v25
	v_mul_f32_e32 v40, 0x3f317218, v24
	v_add_f32_e32 v37, v36, v25
	v_fma_f32 v41, v24, s7, -v40
	v_mul_f32_e32 v38, v37, v37
	v_fmac_f32_e32 v41, 0xb102e308, v24
	v_sub_f32_e32 v24, v37, v36
	v_fmamk_f32 v39, v38, 0x3e9b6dac, v47
	v_sub_f32_e32 v24, v25, v24
	v_add_f32_e32 v25, v40, v41
	v_fmaak_f32 v39, v38, v39, 0x3f2aaada
	v_sub_f32_e32 v36, v25, v40
	v_ldexp_f32 v40, v37, 1
	v_mul_f32_e32 v37, v37, v38
	v_mul_f32_e32 v37, v37, v39
	v_add_f32_e32 v38, v40, v37
	v_sub_f32_e32 v39, v38, v40
	v_ldexp_f32 v24, v24, 1
	v_sub_f32_e32 v37, v37, v39
	v_add_f32_e32 v24, v24, v37
	v_add_f32_e32 v37, v38, v24
	v_sub_f32_e32 v38, v37, v38
	v_sub_f32_e32 v24, v24, v38
	v_add_f32_e32 v38, v25, v37
	v_sub_f32_e32 v39, v38, v25
	v_sub_f32_e32 v40, v38, v39
	v_sub_f32_e32 v36, v41, v36
	v_sub_f32_e32 v25, v25, v40
	v_sub_f32_e32 v37, v37, v39
	v_add_f32_e32 v25, v37, v25
	v_add_f32_e32 v37, v36, v24
	v_sub_f32_e32 v39, v37, v36
	v_sub_f32_e32 v40, v37, v39
	v_sub_f32_e32 v36, v36, v40
	v_sub_f32_e32 v24, v24, v39
	v_add_f32_e32 v25, v37, v25
	v_add_f32_e32 v24, v24, v36
	v_add_f32_e32 v36, v38, v25
	v_sub_f32_e32 v37, v36, v38
	v_sub_f32_e32 v25, v25, v37
	v_add_f32_e32 v24, v24, v25
	v_add_f32_e32 v24, v36, v24
	v_cndmask_b32_e64 v24, v48, v24, s[0:1]
	v_cmp_ngt_f32_e64 s[0:1], -1.0, v27
	s_nop 1
	v_cndmask_b32_e64 v24, v49, v24, s[0:1]
	v_cmp_neq_f32_e64 s[0:1], -1.0, v27
	s_nop 1
	v_cndmask_b32_e64 v24, v248, v24, s[0:1]
	v_cmp_lt_f32_e64 s[0:1], |v27|, s11
	s_nop 1
	v_cndmask_b32_e64 v24, v24, v27, s[0:1]
	v_sub_f32_e32 v24, v26, v24
	v_lshl_add_u64 v[26:27], s[4:5], 0, v[12:13]
	v_add_f32_e32 v24, v23, v24
	s_waitcnt vmcnt(2)
	v_mov_b32_e32 v25, v57
	v_add_f32_e32 v25, v0, v25
	v_min_f32_e32 v36, 0, v25
	v_mul_f32_e64 v25, |v25|, s85
	v_exp_f32_e32 v25, v25
	s_nop 0
	v_add_f32_e32 v37, 1.0, v25
	v_add_f32_e32 v26, -1.0, v37
	v_sub_f32_e32 v27, v26, v37
	v_add_f32_e32 v27, 1.0, v27
	v_sub_f32_e32 v26, v25, v26
	v_add_f32_e32 v38, v26, v27
	v_frexp_mant_f32_e32 v26, v37
	v_cmp_gt_f32_e64 s[0:1], s6, v26
	v_cvt_f64_f32_e32 v[26:27], v37
	v_frexp_exp_i32_f64_e32 v26, v[26:27]
	v_subbrev_co_u32_e64 v26, s[0:1], 0, v26, s[0:1]
	v_sub_u32_e32 v27, 0, v26
	v_ldexp_f32 v37, v37, v27
	v_ldexp_f32 v27, v38, v27
	v_add_f32_e32 v38, -1.0, v37
	v_add_f32_e32 v39, 1.0, v38
	v_sub_f32_e32 v39, v37, v39
	v_add_f32_e32 v39, v27, v39
	v_add_f32_e32 v40, v38, v39
	v_sub_f32_e32 v38, v40, v38
	v_sub_f32_e32 v38, v39, v38
	v_add_f32_e32 v39, 1.0, v37
	v_add_f32_e32 v41, -1.0, v39
	v_sub_f32_e32 v37, v37, v41
	v_add_f32_e32 v27, v27, v37
	v_add_f32_e32 v37, v39, v27
	v_sub_f32_e32 v39, v37, v39
	v_sub_f32_e32 v27, v27, v39
	v_rcp_f32_e32 v39, v37
	v_cvt_f32_i32_e32 v26, v26
	v_cmp_neq_f32_e64 s[0:1], s3, v25
	v_mul_f32_e32 v41, v40, v39
	v_mul_f32_e32 v42, v37, v41
	v_fma_f32 v43, v41, v37, -v42
	v_fmac_f32_e32 v43, v41, v27
	v_add_f32_e32 v44, v42, v43
	v_sub_f32_e32 v45, v40, v44
	v_sub_f32_e32 v40, v40, v45
	v_sub_f32_e32 v42, v44, v42
	v_sub_f32_e32 v40, v40, v44
	v_add_f32_e32 v38, v38, v40
	v_sub_f32_e32 v40, v42, v43
	v_add_f32_e32 v38, v40, v38
	v_add_f32_e32 v40, v45, v38
	v_mul_f32_e32 v42, v39, v40
	v_mul_f32_e32 v43, v37, v42
	v_fma_f32 v37, v42, v37, -v43
	v_fmac_f32_e32 v37, v42, v27
	v_sub_f32_e32 v27, v45, v40
	v_add_f32_e32 v27, v38, v27
	v_add_f32_e32 v38, v43, v37
	v_sub_f32_e32 v44, v40, v38
	v_sub_f32_e32 v40, v40, v44
	v_sub_f32_e32 v43, v38, v43
	v_sub_f32_e32 v38, v40, v38
	v_add_f32_e32 v27, v27, v38
	v_sub_f32_e32 v37, v43, v37
	v_add_f32_e32 v27, v37, v27
	v_add_f32_e32 v37, v41, v42
	v_add_f32_e32 v27, v44, v27
	v_sub_f32_e32 v38, v37, v41
; DI void fox_cumsum(const Params& p, int e) {
;     ...
;     for (int i = 0; i < 8; ++i) { const float x = FF[(size_t)(tid * 8 + i) * 8] + bias; s += fminf(x, 0.f) - log1pf(__expf(-fabsf(x))); v[i] = s; }
	v_mul_f32_e32 v27, v39, v27
	v_sub_f32_e32 v38, v42, v38
	v_add_f32_e32 v27, v38, v27
	v_mul_f32_e32 v41, 0x3f317218, v26
	v_add_f32_e32 v38, v37, v27
	v_fma_f32 v42, v26, s7, -v41
	v_mul_f32_e32 v39, v38, v38
	v_fmac_f32_e32 v42, 0xb102e308, v26
	v_sub_f32_e32 v26, v38, v37
	v_fmamk_f32 v40, v39, 0x3e9b6dac, v47
	v_sub_f32_e32 v26, v27, v26
	v_add_f32_e32 v27, v41, v42
	v_fmaak_f32 v40, v39, v40, 0x3f2aaada
	v_sub_f32_e32 v37, v27, v41
	v_ldexp_f32 v41, v38, 1
	v_mul_f32_e32 v38, v38, v39
	v_mul_f32_e32 v38, v38, v40
	v_add_f32_e32 v39, v41, v38
	v_sub_f32_e32 v40, v39, v41
	v_ldexp_f32 v26, v26, 1
	v_sub_f32_e32 v38, v38, v40
	v_add_f32_e32 v26, v26, v38
	v_add_f32_e32 v38, v39, v26
	v_sub_f32_e32 v39, v38, v39
	v_sub_f32_e32 v26, v26, v39
	v_add_f32_e32 v39, v27, v38
	v_sub_f32_e32 v40, v39, v27
	v_sub_f32_e32 v41, v39, v40
	v_sub_f32_e32 v37, v42, v37
	v_sub_f32_e32 v27, v27, v41
	v_sub_f32_e32 v38, v38, v40
	v_add_f32_e32 v27, v38, v27
	v_add_f32_e32 v38, v37, v26
	v_sub_f32_e32 v40, v38, v37
	v_sub_f32_e32 v41, v38, v40
	v_sub_f32_e32 v37, v37, v41
	v_sub_f32_e32 v26, v26, v40
	v_add_f32_e32 v27, v38, v27
	v_add_f32_e32 v26, v26, v37
	v_add_f32_e32 v37, v39, v27
	v_sub_f32_e32 v38, v37, v39
	v_sub_f32_e32 v27, v27, v38
	v_add_f32_e32 v26, v26, v27
	v_add_f32_e32 v26, v37, v26
	v_cndmask_b32_e64 v26, v48, v26, s[0:1]
	v_cmp_ngt_f32_e64 s[0:1], -1.0, v25
	s_nop 1
	v_cndmask_b32_e64 v26, v49, v26, s[0:1]
	v_cmp_neq_f32_e64 s[0:1], -1.0, v25
	s_nop 1
	v_cndmask_b32_e64 v26, v248, v26, s[0:1]
	v_cmp_lt_f32_e64 s[0:1], |v25|, s11
	s_nop 1
	v_cndmask_b32_e64 v25, v26, v25, s[0:1]
	v_lshl_add_u64 v[26:27], s[4:5], 0, v[14:15]
	v_sub_f32_e32 v25, v36, v25
	v_add_f32_e32 v25, v24, v25
	s_waitcnt vmcnt(1)
	v_mov_b32_e32 v26, v58
	v_add_f32_e32 v26, v0, v26
	v_min_f32_e32 v36, 0, v26
	v_mul_f32_e64 v26, |v26|, s85
	v_exp_f32_e32 v37, v26
	s_nop 0
	v_add_f32_e32 v38, 1.0, v37
	v_add_f32_e32 v26, -1.0, v38
	v_sub_f32_e32 v27, v26, v38
	v_add_f32_e32 v27, 1.0, v27
	v_sub_f32_e32 v26, v37, v26
	v_add_f32_e32 v39, v26, v27
	v_frexp_mant_f32_e32 v26, v38
	v_cmp_gt_f32_e64 s[0:1], s6, v26
	v_cvt_f64_f32_e32 v[26:27], v38
	v_frexp_exp_i32_f64_e32 v26, v[26:27]
	v_subbrev_co_u32_e64 v26, s[0:1], 0, v26, s[0:1]
	v_sub_u32_e32 v27, 0, v26
	v_ldexp_f32 v38, v38, v27
	v_ldexp_f32 v27, v39, v27
	v_add_f32_e32 v39, -1.0, v38
	v_add_f32_e32 v40, 1.0, v39
	v_sub_f32_e32 v40, v38, v40
	v_add_f32_e32 v40, v27, v40
	v_add_f32_e32 v41, v39, v40
	v_sub_f32_e32 v39, v41, v39
	v_sub_f32_e32 v39, v40, v39
	v_add_f32_e32 v40, 1.0, v38
	v_add_f32_e32 v42, -1.0, v40
	v_sub_f32_e32 v38, v38, v42
	v_add_f32_e32 v27, v27, v38
	v_add_f32_e32 v38, v40, v27
	v_sub_f32_e32 v40, v38, v40
	v_sub_f32_e32 v27, v27, v40
	v_rcp_f32_e32 v40, v38
	v_cvt_f32_i32_e32 v26, v26
	v_cmp_neq_f32_e64 s[0:1], s3, v37
	v_mul_f32_e32 v42, v41, v40
	v_mul_f32_e32 v43, v38, v42
	v_fma_f32 v44, v42, v38, -v43
	v_fmac_f32_e32 v44, v42, v27
	v_add_f32_e32 v45, v43, v44
	v_sub_f32_e32 v46, v41, v45
	v_sub_f32_e32 v41, v41, v46
	v_sub_f32_e32 v43, v45, v43
	v_sub_f32_e32 v41, v41, v45
	v_add_f32_e32 v39, v39, v41
	v_sub_f32_e32 v41, v43, v44
	v_add_f32_e32 v39, v41, v39
	v_add_f32_e32 v41, v46, v39
	v_mul_f32_e32 v43, v40, v41
	v_mul_f32_e32 v44, v38, v43
	v_fma_f32 v38, v43, v38, -v44
	v_fmac_f32_e32 v38, v43, v27
	v_sub_f32_e32 v27, v46, v41
	v_add_f32_e32 v27, v39, v27
	v_add_f32_e32 v39, v44, v38
	v_sub_f32_e32 v45, v41, v39
	v_sub_f32_e32 v41, v41, v45
	v_sub_f32_e32 v44, v39, v44
	v_sub_f32_e32 v39, v41, v39
	v_add_f32_e32 v27, v27, v39
	v_sub_f32_e32 v38, v44, v38
	v_add_f32_e32 v27, v38, v27
	v_add_f32_e32 v38, v42, v43
	v_add_f32_e32 v27, v45, v27
	v_sub_f32_e32 v39, v38, v42
	v_mul_f32_e32 v27, v40, v27
	v_sub_f32_e32 v39, v43, v39
	v_add_f32_e32 v27, v39, v27
	v_mul_f32_e32 v42, 0x3f317218, v26
	v_add_f32_e32 v39, v38, v27
	v_fma_f32 v43, v26, s7, -v42
	v_mul_f32_e32 v40, v39, v39
	v_fmac_f32_e32 v43, 0xb102e308, v26
	v_sub_f32_e32 v26, v39, v38
	v_fmamk_f32 v41, v40, 0x3e9b6dac, v47
	v_sub_f32_e32 v26, v27, v26
	v_add_f32_e32 v27, v42, v43
	v_fmaak_f32 v41, v40, v41, 0x3f2aaada
	v_sub_f32_e32 v38, v27, v42
	v_ldexp_f32 v42, v39, 1
	v_mul_f32_e32 v39, v39, v40
	v_mul_f32_e32 v39, v39, v41
	v_add_f32_e32 v40, v42, v39
	v_sub_f32_e32 v41, v40, v42
	v_ldexp_f32 v26, v26, 1
	v_sub_f32_e32 v39, v39, v41
	v_add_f32_e32 v26, v26, v39
	v_add_f32_e32 v39, v40, v26
	v_sub_f32_e32 v40, v39, v40
	v_sub_f32_e32 v26, v26, v40
	v_add_f32_e32 v40, v27, v39
	v_sub_f32_e32 v41, v40, v27
	v_sub_f32_e32 v42, v40, v41
	v_sub_f32_e32 v38, v43, v38
	v_sub_f32_e32 v27, v27, v42
	v_sub_f32_e32 v39, v39, v41
	v_add_f32_e32 v27, v39, v27
	v_add_f32_e32 v39, v38, v26
	v_sub_f32_e32 v41, v39, v38
	v_sub_f32_e32 v42, v39, v41
	v_sub_f32_e32 v38, v38, v42
	v_sub_f32_e32 v26, v26, v41
	v_add_f32_e32 v27, v39, v27
	v_add_f32_e32 v26, v26, v38
	v_add_f32_e32 v38, v40, v27
	v_sub_f32_e32 v39, v38, v40
	v_sub_f32_e32 v27, v27, v39
	v_add_f32_e32 v26, v26, v27
	v_add_f32_e32 v26, v38, v26
	v_cndmask_b32_e64 v26, v48, v26, s[0:1]
	v_cmp_ngt_f32_e64 s[0:1], -1.0, v37
	s_nop 1
	v_cndmask_b32_e64 v26, v49, v26, s[0:1]
	v_cmp_neq_f32_e64 s[0:1], -1.0, v37
	s_nop 1
	v_cndmask_b32_e64 v26, v248, v26, s[0:1]
	v_cmp_lt_f32_e64 s[0:1], |v37|, s11
	s_nop 1
	v_cndmask_b32_e64 v26, v26, v37, s[0:1]
	v_sub_f32_e32 v26, v36, v26
	v_lshl_add_u64 v[36:37], s[4:5], 0, v[16:17]
	v_add_f32_e32 v26, v25, v26
	s_waitcnt vmcnt(0)
; DI float shidx(float v, int src) { return __int_as_float(__builtin_amdgcn_ds_bpermute(src << 2, __float_as_int(v))); }
; DI void fox_cumsum(const Params& p, int e) {
;     ...
;     for (int i = 0; i < 8; ++i) { const float x = FF[(size_t)(tid * 8 + i) * 8] + bias; s += fminf(x, 0.f) - log1pf(__expf(-fabsf(x))); v[i] = s; }
;     float incl = s;
; #pragma unroll
;     for (int o = 1; o < 64; o <<= 1) { const float u = shidx(incl, lane - o); if (lane >= o) incl += u; }
;     if (lane == 63) wsum[w] = incl;
;     __syncthreads();
;     float base = incl - s;
;     for (int q = 0; q < w; ++q) base += wsum[q];
	v_mov_b32_e32 v27, v59
	v_add_f32_e32 v0, v0, v27
	v_min_f32_e32 v27, 0, v0
	v_mul_f32_e64 v0, |v0|, s85
	v_exp_f32_e32 v0, v0
	s_nop 0
	v_add_f32_e32 v38, 1.0, v0
	v_add_f32_e32 v36, -1.0, v38
	v_sub_f32_e32 v37, v36, v38
	v_add_f32_e32 v37, 1.0, v37
	v_sub_f32_e32 v36, v0, v36
	v_add_f32_e32 v39, v36, v37
	v_frexp_mant_f32_e32 v36, v38
	v_cmp_gt_f32_e64 s[0:1], s6, v36
	v_cvt_f64_f32_e32 v[36:37], v38
	v_frexp_exp_i32_f64_e32 v36, v[36:37]
	v_subbrev_co_u32_e64 v36, s[0:1], 0, v36, s[0:1]
	v_sub_u32_e32 v37, 0, v36
	v_ldexp_f32 v38, v38, v37
	v_ldexp_f32 v37, v39, v37
	v_add_f32_e32 v39, -1.0, v38
	v_add_f32_e32 v40, 1.0, v39
	v_sub_f32_e32 v40, v38, v40
	v_add_f32_e32 v40, v37, v40
	v_add_f32_e32 v41, v39, v40
	v_sub_f32_e32 v39, v41, v39
	v_sub_f32_e32 v39, v40, v39
	v_add_f32_e32 v40, 1.0, v38
	v_add_f32_e32 v42, -1.0, v40
	v_sub_f32_e32 v38, v38, v42
	v_add_f32_e32 v37, v37, v38
	v_add_f32_e32 v38, v40, v37
	v_sub_f32_e32 v40, v38, v40
	v_sub_f32_e32 v37, v37, v40
	v_rcp_f32_e32 v40, v38
	v_cvt_f32_i32_e32 v36, v36
	v_cmp_neq_f32_e64 s[0:1], s3, v0
	v_mul_f32_e32 v42, v41, v40
	v_mul_f32_e32 v43, v38, v42
	v_fma_f32 v44, v42, v38, -v43
	v_fmac_f32_e32 v44, v42, v37
	v_add_f32_e32 v45, v43, v44
	v_sub_f32_e32 v46, v41, v45
	v_sub_f32_e32 v41, v41, v46
	v_sub_f32_e32 v43, v45, v43
	v_sub_f32_e32 v41, v41, v45
	v_add_f32_e32 v39, v39, v41
	v_sub_f32_e32 v41, v43, v44
	v_add_f32_e32 v39, v41, v39
	v_add_f32_e32 v41, v46, v39
	v_mul_f32_e32 v43, v40, v41
	v_mul_f32_e32 v44, v38, v43
	v_fma_f32 v38, v43, v38, -v44
	v_fmac_f32_e32 v38, v43, v37
	v_sub_f32_e32 v37, v46, v41
	v_add_f32_e32 v37, v39, v37
	v_add_f32_e32 v39, v44, v38
	v_sub_f32_e32 v45, v41, v39
	v_sub_f32_e32 v41, v41, v45
	v_sub_f32_e32 v44, v39, v44
	v_sub_f32_e32 v39, v41, v39
	v_add_f32_e32 v37, v37, v39
	v_sub_f32_e32 v38, v44, v38
	v_add_f32_e32 v37, v38, v37
	v_add_f32_e32 v38, v42, v43
	v_add_f32_e32 v37, v45, v37
	v_sub_f32_e32 v39, v38, v42
	v_mul_f32_e32 v37, v40, v37
	v_sub_f32_e32 v39, v43, v39
	v_add_f32_e32 v37, v39, v37
	v_mul_f32_e32 v42, 0x3f317218, v36
	v_add_f32_e32 v39, v38, v37
	v_fma_f32 v43, v36, s7, -v42
	v_mul_f32_e32 v40, v39, v39
	v_fmac_f32_e32 v43, 0xb102e308, v36
	v_sub_f32_e32 v36, v39, v38
	v_fmamk_f32 v41, v40, 0x3e9b6dac, v47
	v_sub_f32_e32 v36, v37, v36
	v_add_f32_e32 v37, v42, v43
	v_fmaak_f32 v41, v40, v41, 0x3f2aaada
	v_sub_f32_e32 v38, v37, v42
	v_ldexp_f32 v42, v39, 1
	v_mul_f32_e32 v39, v39, v40
	v_mul_f32_e32 v39, v39, v41
	v_add_f32_e32 v40, v42, v39
	v_sub_f32_e32 v41, v40, v42
	v_ldexp_f32 v36, v36, 1
	v_sub_f32_e32 v39, v39, v41
	v_add_f32_e32 v36, v36, v39
	v_add_f32_e32 v39, v40, v36
	v_sub_f32_e32 v40, v39, v40
	v_sub_f32_e32 v36, v36, v40
	v_add_f32_e32 v40, v37, v39
	v_sub_f32_e32 v41, v40, v37
	v_sub_f32_e32 v42, v40, v41
	v_sub_f32_e32 v38, v43, v38
	v_sub_f32_e32 v37, v37, v42
	v_sub_f32_e32 v39, v39, v41
	v_add_f32_e32 v37, v39, v37
	v_add_f32_e32 v39, v38, v36
	v_sub_f32_e32 v41, v39, v38
	v_sub_f32_e32 v42, v39, v41
	v_sub_f32_e32 v38, v38, v42
	v_sub_f32_e32 v36, v36, v41
	v_add_f32_e32 v37, v39, v37
	v_add_f32_e32 v36, v36, v38
	v_add_f32_e32 v38, v40, v37
	v_sub_f32_e32 v39, v38, v40
	v_sub_f32_e32 v37, v37, v39
	v_add_f32_e32 v36, v36, v37
	v_add_f32_e32 v36, v38, v36
	v_cndmask_b32_e64 v36, v48, v36, s[0:1]
	v_cmp_ngt_f32_e64 s[0:1], -1.0, v0
	s_nop 1
	v_cndmask_b32_e64 v36, v49, v36, s[0:1]
	v_cmp_neq_f32_e64 s[0:1], -1.0, v0
	s_nop 1
	v_cndmask_b32_e64 v36, v248, v36, s[0:1]
	v_cmp_lt_f32_e64 s[0:1], |v0|, s11
	s_nop 1
	v_cndmask_b32_e64 v0, v36, v0, s[0:1]
	v_sub_f32_e32 v0, v27, v0
	v_add_f32_e32 v27, v26, v0
	ds_bpermute_b32 v0, v30, v27
	s_waitcnt lgkmcnt(0)
	v_add_f32_e32 v0, v27, v0
	v_cndmask_b32_e64 v0, v0, v27, s[40:41]
	ds_bpermute_b32 v36, v31, v0
	s_waitcnt lgkmcnt(0)
	v_add_f32_e32 v36, v0, v36
	v_cndmask_b32_e64 v0, v36, v0, s[42:43]
	ds_bpermute_b32 v36, v32, v0
	s_waitcnt lgkmcnt(0)
	v_add_f32_e32 v36, v0, v36
	v_cndmask_b32_e64 v0, v36, v0, s[44:45]
	ds_bpermute_b32 v36, v33, v0
	s_waitcnt lgkmcnt(0)
	v_add_f32_e32 v36, v0, v36
	v_cndmask_b32_e64 v0, v36, v0, s[46:47]
	ds_bpermute_b32 v36, v34, v0
	s_waitcnt lgkmcnt(0)
	v_add_f32_e32 v36, v0, v36
	v_cndmask_b32_e64 v0, v36, v0, s[48:49]
	ds_bpermute_b32 v36, v35, v0
	s_waitcnt lgkmcnt(0)
	v_add_f32_e32 v36, v0, v36
	s_and_saveexec_b64 s[0:1], vcc
	ds_write_b32 v29, v36
	s_or_b64 exec, exec, s[0:1]
	v_cndmask_b32_e64 v0, v36, v0, s[50:51]
	v_sub_f32_e32 v0, v0, v27
	s_waitcnt lgkmcnt(0)
	s_barrier
	s_and_saveexec_b64 s[4:5], s[38:39]
	s_cbranch_execz .LBB0_1970
	s_mov_b32 s3, 0
	s_mov_b64 s[6:7], 0
	v_mov_b32_e32 v36, v28
